# mLSTM next-chunk loads: raw q/k rows issued at 3 points in step 3, V^T tile loads spread in step 4 (instead of one clump in interval A)
# speedup vs baseline: 1.0092x; 1.0028x over previous
.LBB0_207:
	v_mov_b32_e32 v214, v222
	v_mov_b32_e32 v64, s56
	ds_read2_b32 v[164:165], v64 offset0:32 offset1:64
	v_cndmask_b32_e64 v64, 0, 1, s[48:49]
	v_cmp_ne_u32_e64 s[42:43], 1, v64
	s_andn2_b64 vcc, exec, s[48:49]
	v_and_b32_e32 v168, 63, v214
	s_cbranch_vccnz .LBB0_211
	v_mov_b32_e32 v64, s56
	ds_read_b32 v64, v64
	v_lshl_add_u32 v67, v168, 2, 0
	s_waitcnt vmcnt(13) lgkmcnt(2)
	v_add_f32_e32 v66, v213, v98
	v_add_u32_e32 v68, 0x20800, v67
	ds_write_b32 v68, v213
	s_waitcnt lgkmcnt(1)
	v_add_f32_e32 v65, v213, v64
	v_max_f32_e32 v66, v65, v66
	v_add_u32_e32 v68, 0x20900, v67
	ds_write_b32 v68, v99
	v_add_u32_e32 v68, 0x20a00, v67
	v_sub_f32_e32 v65, v65, v66
	ds_write_b32 v68, v66
	v_mul_f32_e32 v68, 0x3fb8aa3b, v65
	v_fma_f32 v69, v65, s0, -v68
	v_rndne_f32_e32 v70, v68
	v_fmac_f32_e32 v69, 0x32a5705f, v65
	v_sub_f32_e32 v68, v68, v70
	v_add_f32_e32 v68, v68, v69
	v_exp_f32_e32 v68, v68
	v_cvt_i32_f32_e32 v69, v70
	v_cmp_ngt_f32_e32 vcc, s28, v65
	v_ldexp_f32 v68, v68, v69
	s_nop 0
	v_cndmask_b32_e32 v68, 0, v68, vcc
	v_cmp_nlt_f32_e32 vcc, s29, v65
	s_nop 1
	v_cndmask_b32_e32 v65, v229, v68, vcc
	v_add_u32_e32 v68, 0x20b00, v67
	ds_write_b32 v68, v65
	v_mul_f32_e32 v65, 0xbfb8aa3b, v66
	v_fma_f32 v68, v66, s94, -v65
	v_rndne_f32_e32 v69, v65
	v_fmac_f32_e32 v68, 0xb2a5705f, v66
	v_sub_f32_e32 v65, v65, v69
	v_add_f32_e32 v65, v65, v68
	v_exp_f32_e32 v65, v65
	v_cvt_i32_f32_e32 v68, v69
	v_cmp_nlt_f32_e32 vcc, s22, v66
	v_ldexp_f32 v65, v65, v68
	s_nop 0
	v_cndmask_b32_e32 v65, 0, v65, vcc
	v_cmp_ngt_f32_e32 vcc, s23, v66
	v_add_u32_e32 v66, 0x20f00, v67
	s_nop 0
	v_cndmask_b32_e32 v65, v229, v65, vcc
	v_cmp_eq_u32_e32 vcc, 0, v168
	ds_write_b32 v66, v65
	s_and_saveexec_b64 s[12:13], vcc
	s_cbranch_execz .LBB0_210
	v_add_f32_e32 v64, v165, v64
	v_sub_f32_e32 v64, v64, v164
	v_mul_f32_e32 v65, 0x3fb8aa3b, v64
	v_fma_f32 v66, v64, s0, -v65
	v_rndne_f32_e32 v67, v65
	v_fmac_f32_e32 v66, 0x32a5705f, v64
	v_sub_f32_e32 v65, v65, v67
	v_add_f32_e32 v65, v65, v66
	v_cvt_i32_f32_e32 v66, v67
	v_exp_f32_e32 v65, v65
	v_cmp_ngt_f32_e32 vcc, s28, v64
	v_ldexp_f32 v65, v65, v66
	s_nop 0
	v_cndmask_b32_e32 v65, 0, v65, vcc
	v_cmp_nlt_f32_e32 vcc, s29, v64
	s_nop 1
	v_cndmask_b32_e32 v64, v229, v65, vcc
	v_mov_b32_e32 v65, s10
	ds_write_b32 v65, v64

.LBB0_211:
	v_and_b32_e32 v215, 31, v214
	v_lshlrev_b32_e32 v64, 3, v215
	v_add_u32_e32 v65, s33, v64
	v_or_b32_e32 v64, s55, v64
	v_cmp_lt_u32_e64 s[44:45], 15, v215
	s_movk_i32 s12, 0x2000
	s_waitcnt vmcnt(13)
	v_lshlrev_b32_e32 v166, 16, v104
	v_cndmask_b32_e64 v169, v64, v65, s[44:45]
	v_lshlrev_b32_e32 v96, 2, v169
	v_lshlrev_b32_e32 v171, 4, v215
	v_add_u32_e32 v171, 0x21a00, v171
	v_and_b32_e32 v167, 0xffff0000, v104
	s_mov_b64 s[12:13], 0x3000
	ds_read_b128 v[84:87], v171 offset:1024
	ds_read_b128 v[88:91], v171
	ds_read_b128 v[92:95], v171 offset:4096
	ds_read_b128 v[156:159], v171 offset:2048
	ds_read_b128 v[160:163], v171 offset:3072
	ds_read_b128 v[64:67], v171 offset:512
	ds_read_b128 v[68:71], v171 offset:4608
	ds_read_b128 v[72:75], v171 offset:1536
	ds_read_b128 v[76:79], v171 offset:2560
	ds_read_b128 v[80:83], v171 offset:3584
	v_lshlrev_b32_e32 v172, 16, v100
	v_and_b32_e32 v173, 0xffff0000, v100
	v_lshlrev_b32_e32 v174, 16, v108
	v_and_b32_e32 v175, 0xffff0000, v108
	v_lshlrev_b32_e32 v176, 16, v112
	v_and_b32_e32 v177, 0xffff0000, v112
	v_lshlrev_b32_e32 v178, 16, v116
	v_and_b32_e32 v179, 0xffff0000, v116
	v_lshlrev_b32_e32 v180, 16, v120
	v_and_b32_e32 v181, 0xffff0000, v120
	v_lshlrev_b32_e32 v182, 16, v124
	v_and_b32_e32 v183, 0xffff0000, v124
	v_ashrrev_i32_e32 v170, 5, v214
	s_movk_i32 s12, 0x440
	v_cmp_gt_u32_e32 vcc, 16, v215
	s_waitcnt lgkmcnt(7)
	v_pk_fma_f32 v[166:167], v[88:89], v[166:167], v[92:93]
	v_pk_fma_f32 v[184:185], v[88:89], v[172:173], v[92:93]
	v_pk_fma_f32 v[186:187], v[88:89], v[174:175], v[92:93]
	v_pk_fma_f32 v[88:89], v[88:89], v[176:177], v[92:93]
	v_pk_fma_f32 v[92:93], v[84:85], v[172:173], v[166:167]
	v_pk_fma_f32 v[166:167], v[84:85], v[174:175], v[184:185]
	v_pk_fma_f32 v[172:173], v[84:85], v[176:177], v[186:187]
	v_pk_fma_f32 v[84:85], v[84:85], v[178:179], v[88:89]
	s_waitcnt lgkmcnt(6)
	v_pk_fma_f32 v[88:89], v[156:157], v[174:175], v[92:93]
	v_pk_fma_f32 v[92:93], v[156:157], v[176:177], v[166:167]
	v_pk_fma_f32 v[166:167], v[156:157], v[178:179], v[172:173]
	v_pk_fma_f32 v[84:85], v[156:157], v[180:181], v[84:85]
	s_waitcnt lgkmcnt(5)
	v_pk_fma_f32 v[88:89], v[160:161], v[176:177], v[88:89]
	v_pk_fma_f32 v[156:157], v[160:161], v[178:179], v[92:93]
	v_pk_fma_f32 v[166:167], v[160:161], v[180:181], v[166:167]
	v_pk_fma_f32 v[160:161], v[160:161], v[182:183], v[84:85]
	v_mul_f32_e32 v84, 0xbfb8aa3b, v88
	v_mul_f32_e32 v85, 0xbfb8aa3b, v89
	v_mul_f32_e32 v92, 0xbfb8aa3b, v156
	v_mul_f32_e32 v93, 0xbfb8aa3b, v157
	v_mul_f32_e32 v96, 0xbfb8aa3b, v166
	v_mul_f32_e32 v171, 0xbfb8aa3b, v167
	v_mul_f32_e32 v172, 0xbfb8aa3b, v160
	v_mul_f32_e32 v173, 0xbfb8aa3b, v161
	v_exp_f32_e32 v84, v84
	v_exp_f32_e32 v85, v85
	v_exp_f32_e32 v92, v92
	v_exp_f32_e32 v93, v93
	v_exp_f32_e32 v96, v96
	v_exp_f32_e32 v171, v171
	v_exp_f32_e32 v172, v172
	v_exp_f32_e32 v173, v173
	v_add_f32_e32 v84, 1.0, v84
	v_add_f32_e32 v85, 1.0, v85
	v_add_f32_e32 v92, 1.0, v92
	v_add_f32_e32 v93, 1.0, v93
	v_add_f32_e32 v96, 1.0, v96
	v_add_f32_e32 v171, 1.0, v171
	v_add_f32_e32 v176, 1.0, v172
	v_add_f32_e32 v177, 1.0, v173
	v_rcp_f32_e32 v84, v84
	v_rcp_f32_e32 v85, v85
	v_rcp_f32_e32 v172, v92
	v_rcp_f32_e32 v173, v93
	v_rcp_f32_e32 v174, v96
	v_rcp_f32_e32 v175, v171
	v_pk_mul_f32 v[92:93], v[88:89], v[84:85]
	v_pk_mul_f32 v[88:89], v[156:157], v[172:173]
	v_lshlrev_b32_e32 v156, 16, v105
	v_and_b32_e32 v157, 0xffff0000, v105
	v_pk_mul_f32 v[84:85], v[166:167], v[174:175]
	v_lshlrev_b32_e32 v166, 16, v101
	v_and_b32_e32 v167, 0xffff0000, v101
	v_pk_fma_f32 v[156:157], v[90:91], v[156:157], v[94:95]
	v_lshlrev_b32_e32 v172, 16, v109
	v_and_b32_e32 v173, 0xffff0000, v109
	v_pk_fma_f32 v[156:157], v[86:87], v[166:167], v[156:157]
	v_lshlrev_b32_e32 v174, 16, v113
	v_and_b32_e32 v175, 0xffff0000, v113
	v_pk_fma_f32 v[156:157], v[158:159], v[172:173], v[156:157]
	v_rcp_f32_e32 v176, v176
	v_pk_fma_f32 v[178:179], v[162:163], v[174:175], v[156:157]
	v_rcp_f32_e32 v177, v177
	v_mul_f32_e32 v96, 0xbfb8aa3b, v178
	v_exp_f32_e32 v96, v96
	v_mul_f32_e32 v156, 0xbfb8aa3b, v179
	v_exp_f32_e32 v171, v156
	v_pk_fma_f32 v[166:167], v[90:91], v[166:167], v[94:95]
	v_pk_mul_f32 v[156:157], v[160:161], v[176:177]
	v_pk_fma_f32 v[166:167], v[86:87], v[172:173], v[166:167]
	v_add_f32_e32 v96, 1.0, v96
	v_lshlrev_b32_e32 v176, 16, v117
	v_and_b32_e32 v177, 0xffff0000, v117
	v_pk_fma_f32 v[166:167], v[158:159], v[174:175], v[166:167]
	v_rcp_f32_e32 v160, v96
	v_add_f32_e32 v96, 1.0, v171
	v_pk_fma_f32 v[166:167], v[162:163], v[176:177], v[166:167]
	v_rcp_f32_e32 v161, v96
	v_mul_f32_e32 v96, 0xbfb8aa3b, v166
	v_exp_f32_e32 v96, v96
	v_mul_f32_e32 v171, 0xbfb8aa3b, v167
	v_exp_f32_e32 v171, v171
	v_pk_fma_f32 v[172:173], v[90:91], v[172:173], v[94:95]
	v_add_f32_e32 v96, 1.0, v96
	v_pk_fma_f32 v[172:173], v[86:87], v[174:175], v[172:173]
	v_lshlrev_b32_e32 v180, 16, v121
	v_and_b32_e32 v181, 0xffff0000, v121
	v_pk_fma_f32 v[172:173], v[158:159], v[176:177], v[172:173]
	v_pk_mul_f32 v[160:161], v[178:179], v[160:161]
	v_rcp_f32_e32 v178, v96
	v_add_f32_e32 v96, 1.0, v171
	v_pk_fma_f32 v[172:173], v[162:163], v[180:181], v[172:173]
	v_rcp_f32_e32 v179, v96
	v_mul_f32_e32 v96, 0xbfb8aa3b, v172
	v_exp_f32_e32 v96, v96
	v_mul_f32_e32 v171, 0xbfb8aa3b, v173
	v_exp_f32_e32 v171, v171
	v_pk_fma_f32 v[90:91], v[90:91], v[174:175], v[94:95]
	v_add_f32_e32 v96, 1.0, v96
	v_pk_fma_f32 v[86:87], v[86:87], v[176:177], v[90:91]
	v_pk_mul_f32 v[166:167], v[166:167], v[178:179]
	v_rcp_f32_e32 v178, v96
	v_add_f32_e32 v96, 1.0, v171
	v_lshlrev_b32_e32 v182, 16, v125
	v_and_b32_e32 v183, 0xffff0000, v125
	v_pk_fma_f32 v[86:87], v[158:159], v[180:181], v[86:87]
	v_rcp_f32_e32 v179, v96
	v_pk_fma_f32 v[90:91], v[162:163], v[182:183], v[86:87]
	v_lshlrev_b32_e32 v158, 16, v106
	v_mul_f32_e32 v86, 0xbfb8aa3b, v90
	v_exp_f32_e32 v94, v86
	v_mul_f32_e32 v86, 0xbfb8aa3b, v91
	v_and_b32_e32 v159, 0xffff0000, v106
	v_exp_f32_e32 v95, v86
	v_lshlrev_b32_e32 v162, 16, v102
	v_and_b32_e32 v163, 0xffff0000, v102
	s_waitcnt lgkmcnt(3)
	v_pk_fma_f32 v[158:159], v[64:65], v[158:159], v[68:69]
	v_pk_mul_f32 v[86:87], v[172:173], v[178:179]
	v_lshlrev_b32_e32 v172, 16, v110
	v_and_b32_e32 v173, 0xffff0000, v110
	s_waitcnt lgkmcnt(2)
	v_pk_fma_f32 v[158:159], v[72:73], v[162:163], v[158:159]
	v_lshlrev_b32_e32 v174, 16, v114
	v_and_b32_e32 v175, 0xffff0000, v114
	s_waitcnt lgkmcnt(1)
	v_pk_fma_f32 v[158:159], v[76:77], v[172:173], v[158:159]
	v_add_f32_e32 v94, 1.0, v94
	s_waitcnt lgkmcnt(0)
	v_pk_fma_f32 v[158:159], v[80:81], v[174:175], v[158:159]
	v_add_f32_e32 v95, 1.0, v95
	v_mul_f32_e32 v96, 0xbfb8aa3b, v158
	v_rcp_f32_e32 v94, v94
	v_rcp_f32_e32 v95, v95
	v_exp_f32_e32 v96, v96
	v_mul_f32_e32 v171, 0xbfb8aa3b, v159
	v_pk_fma_f32 v[162:163], v[64:65], v[162:163], v[68:69]
	v_exp_f32_e32 v171, v171
	v_pk_fma_f32 v[162:163], v[72:73], v[172:173], v[162:163]
	v_lshlrev_b32_e32 v176, 16, v118
	v_and_b32_e32 v177, 0xffff0000, v118
	v_pk_fma_f32 v[162:163], v[76:77], v[174:175], v[162:163]
	v_pk_mul_f32 v[90:91], v[90:91], v[94:95]
	v_pk_fma_f32 v[162:163], v[80:81], v[176:177], v[162:163]
	v_add_f32_e32 v94, 1.0, v96
	v_mul_f32_e32 v96, 0xbfb8aa3b, v162
	v_add_f32_e32 v95, 1.0, v171
	v_exp_f32_e32 v96, v96
	v_mul_f32_e32 v171, 0xbfb8aa3b, v163
	v_rcp_f32_e32 v94, v94
	v_rcp_f32_e32 v95, v95
	v_exp_f32_e32 v171, v171
	v_pk_fma_f32 v[172:173], v[64:65], v[172:173], v[68:69]
	v_add_f32_e32 v96, 1.0, v96
	v_pk_fma_f32 v[172:173], v[72:73], v[174:175], v[172:173]
	v_lshlrev_b32_e32 v178, 16, v122
	v_and_b32_e32 v179, 0xffff0000, v122
	v_pk_fma_f32 v[172:173], v[76:77], v[176:177], v[172:173]
	v_pk_mul_f32 v[94:95], v[158:159], v[94:95]
	v_rcp_f32_e32 v158, v96
	v_add_f32_e32 v96, 1.0, v171
	v_pk_fma_f32 v[172:173], v[80:81], v[178:179], v[172:173]
	v_rcp_f32_e32 v159, v96
	v_mul_f32_e32 v96, 0xbfb8aa3b, v172
	v_exp_f32_e32 v96, v96
	v_mul_f32_e32 v171, 0xbfb8aa3b, v173
	v_exp_f32_e32 v171, v171
	v_pk_fma_f32 v[64:65], v[64:65], v[174:175], v[68:69]
	v_add_f32_e32 v96, 1.0, v96
	v_pk_fma_f32 v[64:65], v[72:73], v[176:177], v[64:65]
	v_lshlrev_b32_e32 v180, 16, v126
	v_and_b32_e32 v181, 0xffff0000, v126
	v_pk_fma_f32 v[64:65], v[76:77], v[178:179], v[64:65]
	v_pk_mul_f32 v[158:159], v[162:163], v[158:159]
	v_rcp_f32_e32 v162, v96
	v_add_f32_e32 v96, 1.0, v171
	v_pk_fma_f32 v[64:65], v[80:81], v[180:181], v[64:65]
	v_rcp_f32_e32 v163, v96
	v_mul_f32_e32 v68, 0xbfb8aa3b, v64
	v_mul_f32_e32 v69, 0xbfb8aa3b, v65
	v_exp_f32_e32 v68, v68
	v_exp_f32_e32 v69, v69
	v_lshlrev_b32_e32 v72, 16, v107
	v_and_b32_e32 v73, 0xffff0000, v107
	v_lshlrev_b32_e32 v80, 16, v103
	v_and_b32_e32 v81, 0xffff0000, v103
	v_pk_fma_f32 v[72:73], v[66:67], v[72:73], v[70:71]
	v_pk_mul_f32 v[76:77], v[172:173], v[162:163]
	v_lshlrev_b32_e32 v162, 16, v111
	v_and_b32_e32 v163, 0xffff0000, v111
	v_pk_fma_f32 v[72:73], v[74:75], v[80:81], v[72:73]
	v_add_f32_e32 v68, 1.0, v68
	v_add_f32_e32 v69, 1.0, v69
	v_lshlrev_b32_e32 v172, 16, v115
	v_and_b32_e32 v173, 0xffff0000, v115
	v_pk_fma_f32 v[72:73], v[78:79], v[162:163], v[72:73]
	v_rcp_f32_e32 v68, v68
	v_rcp_f32_e32 v69, v69
	v_pk_fma_f32 v[174:175], v[82:83], v[172:173], v[72:73]
	v_pk_fma_f32 v[80:81], v[66:67], v[80:81], v[70:71]
	v_mul_f32_e32 v72, 0xbfb8aa3b, v174
	v_exp_f32_e32 v96, v72
	v_mul_f32_e32 v72, 0xbfb8aa3b, v175
	v_exp_f32_e32 v171, v72
	v_pk_fma_f32 v[80:81], v[74:75], v[162:163], v[80:81]
	v_pk_mul_f32 v[72:73], v[64:65], v[68:69]
	v_lshlrev_b32_e32 v68, 16, v119
	v_and_b32_e32 v69, 0xffff0000, v119
	v_pk_fma_f32 v[80:81], v[78:79], v[172:173], v[80:81]
	v_add_f32_e32 v64, 1.0, v96
	v_pk_fma_f32 v[80:81], v[82:83], v[68:69], v[80:81]
	v_add_f32_e32 v65, 1.0, v171
	v_mul_f32_e32 v96, 0xbfb8aa3b, v80
	v_exp_f32_e32 v96, v96
	v_mul_f32_e32 v171, 0xbfb8aa3b, v81
	v_pk_fma_f32 v[162:163], v[66:67], v[162:163], v[70:71]
	v_pk_fma_f32 v[66:67], v[66:67], v[172:173], v[70:71]
	v_exp_f32_e32 v171, v171
	v_lshlrev_b32_e32 v178, 16, v123
	v_and_b32_e32 v179, 0xffff0000, v123
	v_pk_fma_f32 v[66:67], v[74:75], v[68:69], v[66:67]
	v_pk_fma_f32 v[162:163], v[74:75], v[172:173], v[162:163]
	v_lshlrev_b32_e32 v182, 16, v127
	v_and_b32_e32 v183, 0xffff0000, v127
	v_pk_fma_f32 v[66:67], v[78:79], v[178:179], v[66:67]
	v_pk_fma_f32 v[162:163], v[78:79], v[68:69], v[162:163]
	v_pk_fma_f32 v[74:75], v[82:83], v[182:183], v[66:67]
	v_add_f32_e32 v96, 1.0, v96
	v_pk_fma_f32 v[162:163], v[82:83], v[178:179], v[162:163]
	v_mul_f32_e32 v66, 0xbfb8aa3b, v74
	v_rcp_f32_e32 v176, v96
	v_add_f32_e32 v96, 1.0, v171
	v_mul_f32_e32 v171, 0xbfb8aa3b, v162
	v_exp_f32_e32 v66, v66
	v_mul_f32_e32 v67, 0xbfb8aa3b, v75
	v_exp_f32_e32 v171, v171
	v_mul_f32_e32 v177, 0xbfb8aa3b, v163
	v_exp_f32_e32 v67, v67
	v_exp_f32_e32 v181, v177
	v_add_f32_e32 v66, 1.0, v66
	v_rcp_f32_e32 v177, v96
	v_add_f32_e32 v96, 1.0, v171
	v_rcp_f32_e32 v78, v66
	v_add_f32_e32 v66, 1.0, v67
	v_rcp_f32_e32 v64, v64
	v_rcp_f32_e32 v65, v65
	v_rcp_f32_e32 v180, v96
	v_add_f32_e32 v96, 1.0, v181
	v_rcp_f32_e32 v79, v66
	v_rcp_f32_e32 v181, v96
	v_pk_mul_f32 v[70:71], v[174:175], v[64:65]
	v_pk_mul_f32 v[68:69], v[80:81], v[176:177]
	v_pk_mul_f32 v[64:65], v[74:75], v[78:79]
	v_lshlrev_b32_e32 v74, 4, v215
	v_mul_lo_u32 v75, v170, s12
	v_pk_mul_f32 v[66:67], v[162:163], v[180:181]
	v_add3_u32 v96, 0, v74, v75
	s_and_saveexec_b64 s[12:13], vcc
	s_xor_b64 s[12:13], exec, s[12:13]
	s_cbranch_execz .LBB0_213
	v_cvt_pk_bf16_f32 v78, v92, v93
	v_cvt_pk_bf16_f32 v79, v160, v161
	v_cvt_pk_bf16_f32 v80, v94, v95
	v_cvt_pk_bf16_f32 v81, v70, v71
	ds_write_b128 v96, v[78:81]
	v_cvt_pk_bf16_f32 v81, v68, v69
	v_cvt_pk_bf16_f32 v68, v84, v85
	v_cvt_pk_bf16_f32 v69, v86, v87
	v_cvt_pk_bf16_f32 v70, v76, v77
	v_cvt_pk_bf16_f32 v71, v66, v67
	v_cvt_pk_bf16_f32 v78, v88, v89
	v_cvt_pk_bf16_f32 v79, v166, v167
	v_cvt_pk_bf16_f32 v80, v158, v159
	ds_write_b128 v96, v[68:71] offset:544
	v_cvt_pk_bf16_f32 v66, v156, v157
	v_cvt_pk_bf16_f32 v67, v90, v91
	v_cvt_pk_bf16_f32 v68, v72, v73
	v_cvt_pk_bf16_f32 v69, v64, v65
	ds_write_b128 v96, v[78:81] offset:272
	ds_write_b128 v96, v[66:69] offset:816

.LBB0_224:
	v_and_b32_e32 v73, 15, v214
	v_or_b32_e32 v64, s17, v73
	s_waitcnt lgkmcnt(0)
	s_barrier
	s_cmpk_eq_i32 s82, 0x7c0
	s_cbranch_scc1 .Lmls_0
	buffer_load_dwordx4 v[104:107], v104, s[76:79], 0 offen offset:2048 sc1
	buffer_load_dwordx4 v[100:103], v100, s[76:79], 0 offen sc1
.Lmls_0:
	v_mul_lo_u32 v64, v64, s1
	v_add_u32_e32 v64, 0, v64
	v_and_b32_e32 v72, 48, v214
	v_lshrrev_b32_e32 v65, 2, v214
	v_and_or_b32 v70, v65, 12, s17
	v_cmp_eq_u32_e64 s[42:43], 0, v73
	s_add_i32 s15, 0, 0x16000
	s_mov_b64 s[12:13], -1
	s_andn2_b64 vcc, exec, s[52:53]
	v_add_u32_e32 v71, v64, v72
	s_cbranch_vccz .LBB0_228
	v_lshl_add_u32 v64, v73, 1, s15
	s_and_b64 vcc, exec, s[12:13]
	v_mul_lo_u32 v74, v70, s93
	s_cbranch_vccnz .LBB0_245

.LBB0_264:
	s_cmpk_eq_i32 s82, 0x7c0
	s_cbranch_scc1 .Lmls_1
	buffer_load_dwordx4 v[108:111], v108, s[76:79], 0 offen offset:2048 sc1
	buffer_load_dwordx4 v[112:115], v112, s[76:79], 0 offen sc1
	buffer_load_dwordx4 v[116:119], v116, s[76:79], 0 offen offset:2048 sc1

.LBB0_266:
	s_or_b64 exec, exec, s[12:13]
	s_cmpk_eq_i32 s82, 0x7c0
	s_cbranch_scc1 .Lmls_2
	buffer_load_dwordx4 v[120:123], v120, s[76:79], 0 offen sc1
	buffer_load_dwordx4 v[124:127], v124, s[76:79], 0 offen offset:2048 sc1
.Lmls_2:
	s_add_u32 s12, s74, s4
	s_addc_u32 s13, s75, s31
	s_waitcnt lgkmcnt(0)
	v_lshl_add_u64 v[64:65], s[12:13], 0, v[96:97]
	v_add_co_u32_e32 v66, vcc, 0xf000000, v64
	s_waitcnt lgkmcnt(0)
	s_barrier
	v_lshrrev_b32_e32 v218, 5, v168
	s_nop 0
	v_addc_co_u32_e32 v67, vcc, 0, v65, vcc
	global_load_dwordx2 v[206:207], v[66:67], off sc1
	global_load_dwordx2 v[204:205], v[66:67], off offset:2048 sc1
	v_add_co_u32_e32 v66, vcc, 0xf001000, v64
	v_lshlrev_b32_e32 v217, 4, v218
	s_nop 0
	v_addc_co_u32_e32 v67, vcc, 0, v65, vcc
	global_load_dwordx2 v[202:203], v[66:67], off sc1
	global_load_dwordx2 v[200:201], v[66:67], off offset:2048 sc1
	v_add_co_u32_e32 v66, vcc, 0xf002000, v64
	v_add_u32_e32 v208, 0, v217
	s_nop 0
	v_addc_co_u32_e32 v67, vcc, 0, v65, vcc
	v_add_co_u32_e32 v64, vcc, 0xf003000, v64
	global_load_dwordx2 v[198:199], v[66:67], off sc1
	global_load_dwordx2 v[196:197], v[66:67], off offset:2048 sc1
	v_addc_co_u32_e32 v65, vcc, 0, v65, vcc
	global_load_dwordx2 v[194:195], v[64:65], off sc1
	global_load_dwordx2 v[192:193], v[64:65], off offset:2048 sc1
	v_lshlrev_b32_e32 v64, 4, v168
	global_load_dwordx4 v[152:155], v64, s[50:51]
	v_mov_b32_e32 v64, s10
	ds_read_b32 v96, v64
	v_or_b32_e32 v64, s11, v215
	v_lshlrev_b32_e32 v68, 3, v218
	v_mul_u32_u24_e32 v69, 0x110, v215
	v_mad_u64_u32 v[64:65], s[12:13], v64, s93, v[208:209]
	v_add3_u32 v176, 0, v68, v69
	ds_read_b128 v[168:171], v64 offset:53248
	ds_read_b128 v[164:167], v64 offset:53280
	ds_read_b128 v[160:163], v64 offset:53312
	ds_read_b128 v[156:159], v64 offset:53344
	v_add_u32_e32 v177, 0x2000, v176
	s_add_i32 s12, 0, 0x20b00
	v_add_u32_e32 v220, s12, v217
	v_add_u32_e32 v219, s15, v217
	s_add_i32 s13, 0, 0x20d00
	s_add_i32 s15, 0, 0x20e00
	s_add_i32 s42, 0, 0x20f00
	s_movk_i32 s43, 0x840
	v_or_b32_e32 v216, 32, v215
	ds_read2_b64 v[232:235], v176 offset0:0 offset1:2
	ds_read2_b64 v[236:239], v177 offset0:64 offset1:66
	ds_read2_b64 v[240:243], v176 offset0:4 offset1:6
	ds_read2_b64 v[180:183], v177 offset0:68 offset1:70
	v_cvt_pk_bf16_f32 v172, v0, v1
	v_cvt_pk_bf16_f32 v173, v2, v3
	v_cvt_pk_bf16_f32 v174, v4, v5
	v_cvt_pk_bf16_f32 v175, v6, v7
	s_nop 0
	s_waitcnt lgkmcnt(3)
	v_mfma_f32_32x32x16_bf16 v[80:95], v[232:235], v[172:175], 0
	ds_read2_b64 v[232:235], v176 offset0:8 offset1:10
	s_waitcnt lgkmcnt(3)
	v_mfma_f32_32x32x16_bf16 v[64:79], v[236:239], v[172:175], 0
	ds_read2_b64 v[236:239], v177 offset0:72 offset1:74
	v_cvt_pk_bf16_f32 v244, v8, v9
	v_cvt_pk_bf16_f32 v245, v10, v11
	v_cvt_pk_bf16_f32 v246, v12, v13
	v_cvt_pk_bf16_f32 v247, v14, v15
	v_pk_mul_f32 v[0:1], v[0:1], v[96:97] op_sel_hi:[1,0]
	v_pk_mul_f32 v[2:3], v[2:3], v[96:97] op_sel_hi:[1,0]
	v_pk_mul_f32 v[4:5], v[4:5], v[96:97] op_sel_hi:[1,0]
	v_pk_mul_f32 v[6:7], v[6:7], v[96:97] op_sel_hi:[1,0]
	s_waitcnt lgkmcnt(3)
	v_mfma_f32_32x32x16_bf16 v[80:95], v[240:243], v[244:247], v[80:95]
	ds_read2_b64 v[240:243], v176 offset0:12 offset1:14
	s_waitcnt lgkmcnt(3)
	v_mfma_f32_32x32x16_bf16 v[64:79], v[180:183], v[244:247], v[64:79]
	ds_read2_b64 v[180:183], v177 offset0:76 offset1:78
	v_cvt_pk_bf16_f32 v172, v16, v17
	v_cvt_pk_bf16_f32 v173, v18, v19
	v_cvt_pk_bf16_f32 v174, v20, v21
	v_cvt_pk_bf16_f32 v175, v22, v23
	v_pk_mul_f32 v[8:9], v[8:9], v[96:97] op_sel_hi:[1,0]
	v_pk_mul_f32 v[10:11], v[10:11], v[96:97] op_sel_hi:[1,0]
	v_pk_mul_f32 v[12:13], v[12:13], v[96:97] op_sel_hi:[1,0]
	v_pk_mul_f32 v[14:15], v[14:15], v[96:97] op_sel_hi:[1,0]
	s_waitcnt lgkmcnt(3)
	v_mfma_f32_32x32x16_bf16 v[80:95], v[232:235], v[172:175], v[80:95]
	ds_read2_b64 v[232:235], v176 offset0:16 offset1:18
	s_waitcnt lgkmcnt(3)
	v_mfma_f32_32x32x16_bf16 v[64:79], v[236:239], v[172:175], v[64:79]
	ds_read2_b64 v[236:239], v177 offset0:80 offset1:82
	v_cvt_pk_bf16_f32 v244, v24, v25
	v_cvt_pk_bf16_f32 v245, v26, v27
	v_cvt_pk_bf16_f32 v246, v28, v29
	v_cvt_pk_bf16_f32 v247, v30, v31
	v_pk_mul_f32 v[16:17], v[16:17], v[96:97] op_sel_hi:[1,0]
	v_pk_mul_f32 v[18:19], v[18:19], v[96:97] op_sel_hi:[1,0]
	v_pk_mul_f32 v[20:21], v[20:21], v[96:97] op_sel_hi:[1,0]
	v_pk_mul_f32 v[22:23], v[22:23], v[96:97] op_sel_hi:[1,0]
	s_waitcnt lgkmcnt(3)
	v_mfma_f32_32x32x16_bf16 v[80:95], v[240:243], v[244:247], v[80:95]
	ds_read2_b64 v[240:243], v176 offset0:20 offset1:22
	s_waitcnt lgkmcnt(3)
	v_mfma_f32_32x32x16_bf16 v[64:79], v[180:183], v[244:247], v[64:79]
	ds_read2_b64 v[180:183], v177 offset0:84 offset1:86
	v_cvt_pk_bf16_f32 v172, v32, v33
	v_cvt_pk_bf16_f32 v173, v34, v35
	v_cvt_pk_bf16_f32 v174, v36, v37
	v_cvt_pk_bf16_f32 v175, v38, v39
	v_pk_mul_f32 v[24:25], v[24:25], v[96:97] op_sel_hi:[1,0]
	v_pk_mul_f32 v[26:27], v[26:27], v[96:97] op_sel_hi:[1,0]
	v_pk_mul_f32 v[28:29], v[28:29], v[96:97] op_sel_hi:[1,0]
	v_pk_mul_f32 v[30:31], v[30:31], v[96:97] op_sel_hi:[1,0]
	s_waitcnt lgkmcnt(3)
	v_mfma_f32_32x32x16_bf16 v[80:95], v[232:235], v[172:175], v[80:95]
	ds_read2_b64 v[232:235], v176 offset0:24 offset1:26
	s_waitcnt lgkmcnt(3)
	v_mfma_f32_32x32x16_bf16 v[64:79], v[236:239], v[172:175], v[64:79]
	ds_read2_b64 v[236:239], v177 offset0:88 offset1:90
	v_cvt_pk_bf16_f32 v244, v40, v41
	v_cvt_pk_bf16_f32 v245, v42, v43
	v_cvt_pk_bf16_f32 v246, v44, v45
	v_cvt_pk_bf16_f32 v247, v46, v47
	v_pk_mul_f32 v[32:33], v[32:33], v[96:97] op_sel_hi:[1,0]
	v_pk_mul_f32 v[34:35], v[34:35], v[96:97] op_sel_hi:[1,0]
	v_pk_mul_f32 v[36:37], v[36:37], v[96:97] op_sel_hi:[1,0]
	v_pk_mul_f32 v[38:39], v[38:39], v[96:97] op_sel_hi:[1,0]
	s_waitcnt lgkmcnt(3)
	v_mfma_f32_32x32x16_bf16 v[80:95], v[240:243], v[244:247], v[80:95]
	ds_read2_b64 v[240:243], v176 offset0:28 offset1:30
	s_waitcnt lgkmcnt(3)
	v_mfma_f32_32x32x16_bf16 v[64:79], v[180:183], v[244:247], v[64:79]
	ds_read2_b64 v[180:183], v177 offset0:92 offset1:94
	v_cvt_pk_bf16_f32 v172, v48, v49
	v_cvt_pk_bf16_f32 v173, v50, v51
	v_cvt_pk_bf16_f32 v174, v52, v53
	v_cvt_pk_bf16_f32 v175, v54, v55
	v_pk_mul_f32 v[40:41], v[40:41], v[96:97] op_sel_hi:[1,0]
	v_pk_mul_f32 v[42:43], v[42:43], v[96:97] op_sel_hi:[1,0]
	v_pk_mul_f32 v[44:45], v[44:45], v[96:97] op_sel_hi:[1,0]
	v_pk_mul_f32 v[46:47], v[46:47], v[96:97] op_sel_hi:[1,0]
	s_waitcnt lgkmcnt(3)
	v_mfma_f32_32x32x16_bf16 v[80:95], v[232:235], v[172:175], v[80:95]
	s_waitcnt lgkmcnt(2)
	v_mfma_f32_32x32x16_bf16 v[64:79], v[236:239], v[172:175], v[64:79]
	v_cvt_pk_bf16_f32 v244, v56, v57
	v_cvt_pk_bf16_f32 v245, v58, v59
	v_cvt_pk_bf16_f32 v246, v60, v61
	v_cvt_pk_bf16_f32 v247, v62, v63
	v_pk_mul_f32 v[48:49], v[48:49], v[96:97] op_sel_hi:[1,0]
	v_pk_mul_f32 v[50:51], v[50:51], v[96:97] op_sel_hi:[1,0]
	v_pk_mul_f32 v[52:53], v[52:53], v[96:97] op_sel_hi:[1,0]
	v_pk_mul_f32 v[54:55], v[54:55], v[96:97] op_sel_hi:[1,0]
	s_waitcnt lgkmcnt(1)
	v_mfma_f32_32x32x16_bf16 v[80:95], v[240:243], v[244:247], v[80:95]
	v_pk_mul_f32 v[56:57], v[56:57], v[96:97] op_sel_hi:[1,0]
	v_pk_mul_f32 v[58:59], v[58:59], v[96:97] op_sel_hi:[1,0]
	v_pk_mul_f32 v[60:61], v[60:61], v[96:97] op_sel_hi:[1,0]
	v_pk_mul_f32 v[62:63], v[62:63], v[96:97] op_sel_hi:[1,0]
	v_lshl_add_u32 v176, v215, 1, s2
	v_mad_u32_u24 v177, v215, s93, v219
	s_waitcnt lgkmcnt(0)
	v_mfma_f32_32x32x16_bf16 v[64:79], v[180:183], v[244:247], v[64:79]
	ds_read_b128 v[172:175], v220
	ds_read_b128 v[232:235], v220 offset:32
	ds_read_b128 v[236:239], v220 offset:64
	ds_read_b128 v[240:243], v220 offset:96
	s_waitcnt lgkmcnt(3)
	v_pk_mul_f32 v[82:83], v[82:83], v[174:175]
	s_waitcnt lgkmcnt(2)
	v_pk_mul_f32 v[86:87], v[86:87], v[234:235]
	s_waitcnt lgkmcnt(1)
	v_pk_mul_f32 v[90:91], v[90:91], v[238:239]
	v_pk_mul_f32 v[88:89], v[88:89], v[236:237]
	v_pk_mul_f32 v[84:85], v[84:85], v[232:233]
	ds_read_b128 v[232:235], v177
	ds_read_b128 v[236:239], v177 offset:32
	s_waitcnt lgkmcnt(2)
	v_pk_mul_f32 v[94:95], v[94:95], v[242:243]
	v_pk_mul_f32 v[92:93], v[92:93], v[240:241]
	v_pk_mul_f32 v[80:81], v[80:81], v[172:173]
	s_waitcnt lgkmcnt(1)
	s_nop 0
	v_mfma_f32_32x32x16_bf16 v[80:95], v[232:235], v[168:171], v[80:95]
	ds_read_b128 v[232:235], v177 offset:64
	s_waitcnt lgkmcnt(1)
	v_mfma_f32_32x32x16_bf16 v[80:95], v[236:239], v[164:167], v[80:95]
	s_waitcnt lgkmcnt(0)
	v_mfma_f32_32x32x16_bf16 v[80:95], v[232:235], v[160:163], v[80:95]
	ds_read_b128 v[232:235], v177 offset:96
	v_add_u32_e32 v177, s13, v217
	s_waitcnt lgkmcnt(0)
	v_mfma_f32_32x32x16_bf16 v[80:95], v[232:235], v[156:159], v[80:95]
	s_cmpk_eq_i32 s82, 0x7c0
	s_cbranch_scc1 .Lmls_3
	buffer_load_dwordx4 v[128:131], v128, s[76:79], 0 offen sc1
.Lmls_3:
	ds_read_b128 v[232:235], v177
	v_add_u32_e32 v177, s15, v217
	ds_read_b128 v[236:239], v177
	v_add_u32_e32 v177, s42, v217
	ds_read_b128 v[240:243], v177
	s_waitcnt lgkmcnt(1)
	v_fma_f32 v172, v172, v232, v236
	v_fmac_f32_e32 v239, v175, v235
	s_waitcnt lgkmcnt(0)
	v_max_f32_e32 v177, v240, v240
	v_max_f32_e64 v172, |v172|, v177
	v_rcp_f32_e32 v172, v172
	s_nop 0
	v_mul_f32_e32 v80, v80, v172
	v_cvt_pk_bf16_f32 v172, v80, s0
	v_mad_u32_u24 v80, v218, s43, v176
	ds_write_b16 v80, v172
	v_fma_f32 v172, v173, v233, v237
	v_max_f32_e32 v173, v241, v241
	v_max_f32_e64 v172, |v172|, v173
	v_rcp_f32_e32 v172, v172
	s_nop 0
	v_mul_f32_e32 v81, v81, v172
	v_cvt_pk_bf16_f32 v81, v81, s0
	ds_write_b16 v80, v81 offset:528
	v_fma_f32 v81, v174, v234, v238
	v_max_f32_e32 v172, v242, v242
	v_max_f32_e64 v81, |v81|, v172
	v_rcp_f32_e32 v81, v81
	s_nop 0
	v_mul_f32_e32 v81, v82, v81
	v_cvt_pk_bf16_f32 v81, v81, s0
	ds_write_b16 v80, v81 offset:1056
	v_max_f32_e32 v81, v243, v243
	v_max_f32_e64 v81, |v239|, v81
	v_rcp_f32_e32 v81, v81
	s_nop 0
	v_mul_f32_e32 v81, v83, v81
	v_cvt_pk_bf16_f32 v81, v81, s0
	ds_write_b16 v80, v81 offset:1584
	v_lshl_or_b32 v81, v218, 2, 8
	v_lshlrev_b32_e32 v82, 2, v81
	v_add_u32_e32 v83, s12, v82
	ds_read_b128 v[172:175], v83
	v_add_u32_e32 v83, s13, v82
	ds_read_b128 v[232:235], v83
	v_add_u32_e32 v83, s15, v82
	v_add_u32_e32 v82, s42, v82
	ds_read_b128 v[236:239], v83
	ds_read_b128 v[240:243], v82
	v_mad_u32_u24 v81, v81, s85, v176
	s_waitcnt lgkmcnt(1)
	v_fma_f32 v82, v172, v232, v236
	s_waitcnt lgkmcnt(0)
	v_max_f32_e32 v83, v240, v240
	v_max_f32_e64 v82, |v82|, v83
	v_rcp_f32_e32 v82, v82
	v_max_f32_e32 v83, v241, v241
	v_fmac_f32_e32 v239, v175, v235
	v_mul_f32_e32 v82, v84, v82
	v_cvt_pk_bf16_f32 v82, v82, s0
	ds_write_b16 v81, v82
	v_fma_f32 v82, v173, v233, v237
	v_max_f32_e64 v82, |v82|, v83
	v_rcp_f32_e32 v82, v82
	v_max_f32_e32 v83, v242, v242
	v_mul_f32_e32 v82, v85, v82
	v_cvt_pk_bf16_f32 v82, v82, s0
	ds_write_b16 v80, v82 offset:4752
	v_fma_f32 v82, v174, v234, v238
	v_max_f32_e64 v82, |v82|, v83
	v_rcp_f32_e32 v82, v82
	s_nop 0
	v_mul_f32_e32 v82, v86, v82
	v_cvt_pk_bf16_f32 v82, v82, s0
	ds_write_b16 v80, v82 offset:5280
	v_max_f32_e32 v82, v243, v243
	v_max_f32_e64 v82, |v239|, v82
	v_rcp_f32_e32 v82, v82
	v_or_b32_e32 v86, 64, v217
	v_mul_f32_e32 v82, v87, v82
	v_cvt_pk_bf16_f32 v82, v82, s0
	ds_write_b16 v80, v82 offset:5808
	s_cmpk_eq_i32 s82, 0x7c0
	s_cbranch_scc1 .Lmls_4
	buffer_load_dwordx4 v[140:143], v140, s[76:79], 0 offen sc1
.Lmls_4:
	v_add_u32_e32 v87, s13, v86
	v_add_u32_e32 v82, s12, v86
	ds_read_b128 v[172:175], v87
	v_add_u32_e32 v87, s15, v86
	v_add_u32_e32 v86, s42, v86
	ds_read_b128 v[82:85], v82
	ds_read_b128 v[236:239], v86
	ds_read_b128 v[232:235], v87
	s_waitcnt lgkmcnt(1)
	v_max_f32_e32 v86, v236, v236
	s_waitcnt lgkmcnt(0)
	v_fma_f32 v82, v82, v172, v232
	v_max_f32_e64 v82, |v82|, v86
	v_rcp_f32_e32 v82, v82
	v_fmac_f32_e32 v235, v85, v175
	v_mul_f32_e32 v82, v88, v82
	v_cvt_pk_bf16_f32 v82, v82, s0
	ds_write_b16 v81, v82 offset:4224
	v_fma_f32 v82, v83, v173, v233
	v_max_f32_e32 v83, v237, v237
	v_max_f32_e64 v82, |v82|, v83
	v_rcp_f32_e32 v82, v82
	v_max_f32_e32 v83, v238, v238
	v_mul_f32_e32 v82, v89, v82
	v_cvt_pk_bf16_f32 v82, v82, s0
	ds_write_b16 v80, v82 offset:8976
	v_fma_f32 v82, v84, v174, v234
	v_max_f32_e64 v82, |v82|, v83
	v_rcp_f32_e32 v82, v82
	s_nop 0
	v_mul_f32_e32 v82, v90, v82
	v_cvt_pk_bf16_f32 v82, v82, s0
	ds_write_b16 v80, v82 offset:9504
	v_max_f32_e32 v82, v239, v239
	v_max_f32_e64 v82, |v235|, v82
	v_rcp_f32_e32 v82, v82
	v_or_b32_e32 v90, 0x60, v217
	v_add_u32_e32 v86, s13, v90
	v_mul_f32_e32 v82, v91, v82
	v_cvt_pk_bf16_f32 v82, v82, s0
	ds_write_b16 v80, v82 offset:10032
	v_add_u32_e32 v82, s12, v90
	v_add_u32_e32 v91, s15, v90
	v_add_u32_e32 v90, s42, v90
	ds_read_b128 v[82:85], v82
	ds_read_b128 v[86:89], v86
	ds_read_b128 v[172:175], v91
	ds_read_b128 v[232:235], v90
	s_waitcnt lgkmcnt(1)
	v_fma_f32 v82, v82, v86, v172
	s_waitcnt lgkmcnt(0)
	v_max_f32_e32 v86, v232, v232
	v_max_f32_e64 v82, |v82|, v86
	v_rcp_f32_e32 v82, v82
	v_fmac_f32_e32 v175, v85, v89
	v_mul_f32_e32 v82, v92, v82
	v_cvt_pk_bf16_f32 v82, v82, s0
	ds_write_b16 v81, v82 offset:8448
	v_fma_f32 v82, v83, v87, v173
	v_max_f32_e32 v83, v233, v233
	v_max_f32_e64 v82, |v82|, v83
	v_rcp_f32_e32 v82, v82
	v_max_f32_e32 v83, v234, v234
	v_mul_f32_e32 v82, v93, v82
	v_cvt_pk_bf16_f32 v82, v82, s0
	ds_write_b16 v80, v82 offset:13200
	v_fma_f32 v82, v84, v88, v174
	v_max_f32_e64 v82, |v82|, v83
	v_rcp_f32_e32 v82, v82
	s_nop 0
	v_mul_f32_e32 v82, v94, v82
	v_cvt_pk_bf16_f32 v82, v82, s0
	ds_write_b16 v80, v82 offset:13728
	v_max_f32_e32 v82, v235, v235
	v_max_f32_e64 v82, |v175|, v82
	v_rcp_f32_e32 v82, v82
	v_mad_u32_u24 v94, v216, s93, v219
	v_mul_f32_e32 v82, v95, v82
	v_cvt_pk_bf16_f32 v82, v82, s0
	ds_write_b16 v80, v82 offset:14256
	s_cmpk_eq_i32 s82, 0x7c0
	s_cbranch_scc1 .Lmls_5
	buffer_load_dwordx4 v[144:147], v144, s[76:79], 0 offen sc1
.Lmls_5:
	ds_read_b128 v[82:85], v220 offset:128
	ds_read_b128 v[86:89], v220 offset:160
	ds_read_b128 v[90:93], v220 offset:192
	ds_read_b128 v[172:175], v220 offset:224
	s_waitcnt lgkmcnt(3)
	v_pk_mul_f32 v[66:67], v[66:67], v[84:85]
	s_waitcnt lgkmcnt(2)
	v_pk_mul_f32 v[68:69], v[68:69], v[86:87]
	s_waitcnt lgkmcnt(1)
	v_pk_mul_f32 v[72:73], v[72:73], v[90:91]
	v_pk_mul_f32 v[74:75], v[74:75], v[92:93]
	v_pk_mul_f32 v[70:71], v[70:71], v[88:89]
	ds_read_b128 v[86:89], v94
	ds_read_b128 v[90:93], v94 offset:32
	s_waitcnt lgkmcnt(2)
	v_pk_mul_f32 v[76:77], v[76:77], v[172:173]
	v_pk_mul_f32 v[78:79], v[78:79], v[174:175]
	v_pk_mul_f32 v[64:65], v[64:65], v[82:83]
	s_waitcnt lgkmcnt(1)
	s_nop 0
	v_mfma_f32_32x32x16_bf16 v[64:79], v[86:89], v[168:171], v[64:79]
	ds_read_b128 v[86:89], v94 offset:64
	s_waitcnt lgkmcnt(1)
	v_mfma_f32_32x32x16_bf16 v[64:79], v[90:93], v[164:167], v[64:79]
	s_waitcnt lgkmcnt(0)
	v_mfma_f32_32x32x16_bf16 v[64:79], v[86:89], v[160:163], v[64:79]
	ds_read_b128 v[86:89], v94 offset:96
	v_or_b32_e32 v94, 0x80, v217
	v_add_u32_e32 v90, s15, v94
	ds_read_b128 v[90:93], v90
	s_waitcnt lgkmcnt(1)
	v_mfma_f32_32x32x16_bf16 v[64:79], v[86:89], v[156:159], v[64:79]
	v_add_u32_e32 v86, s13, v94
	v_add_u32_e32 v94, s42, v94
	ds_read_b128 v[86:89], v86
	ds_read_b128 v[172:175], v94
	s_waitcnt lgkmcnt(1)
	v_fma_f32 v82, v82, v86, v90
	s_waitcnt lgkmcnt(0)
	v_max_f32_e32 v86, v172, v172
	v_max_f32_e64 v82, |v82|, v86
	v_rcp_f32_e32 v82, v82
	v_fmac_f32_e32 v93, v85, v89
	v_or_b32_e32 v90, 0xa0, v217
	v_add_u32_e32 v86, s15, v90
	v_mul_f32_e32 v64, v64, v82
	v_cvt_pk_bf16_f32 v64, v64, s0
	ds_write_b16 v81, v64 offset:12672
	v_fma_f32 v64, v83, v87, v91
	v_max_f32_e32 v82, v173, v173
	v_max_f32_e64 v64, |v64|, v82
	v_rcp_f32_e32 v64, v64
	v_add_u32_e32 v82, s13, v90
	v_mul_f32_e32 v64, v65, v64
	v_cvt_pk_bf16_f32 v64, v64, s0
	ds_write_b16 v80, v64 offset:17424
	v_fma_f32 v64, v84, v88, v92
	v_max_f32_e32 v65, v174, v174
	v_max_f32_e64 v64, |v64|, v65
	v_rcp_f32_e32 v64, v64
	s_nop 0
	v_mul_f32_e32 v64, v66, v64
	v_cvt_pk_bf16_f32 v64, v64, s0
	ds_write_b16 v80, v64 offset:17952
	v_max_f32_e32 v64, v175, v175
	v_max_f32_e64 v64, |v93|, v64
	v_rcp_f32_e32 v64, v64
	s_nop 0
	v_mul_f32_e32 v64, v67, v64
	v_cvt_pk_bf16_f32 v64, v64, s0
	ds_write_b16 v80, v64 offset:18480
	s_cmpk_eq_i32 s82, 0x7c0
	s_cbranch_scc1 .Lmls_6
	buffer_load_dwordx4 v[148:151], v148, s[76:79], 0 offen sc1
.Lmls_6:
	v_add_u32_e32 v64, s12, v90
	v_add_u32_e32 v90, s42, v90
	ds_read_b128 v[64:67], v64
	ds_read_b128 v[82:85], v82
	ds_read_b128 v[86:89], v86
	ds_read_b128 v[90:93], v90
	s_waitcnt lgkmcnt(1)
	v_fma_f32 v64, v64, v82, v86
	s_waitcnt lgkmcnt(0)
	v_max_f32_e32 v82, v90, v90
	v_max_f32_e64 v64, |v64|, v82
	v_rcp_f32_e32 v64, v64
	v_fmac_f32_e32 v89, v67, v85
	v_or_b32_e32 v86, 0xc0, v217
	v_add_u32_e32 v82, s15, v86
	v_mul_f32_e32 v64, v68, v64
	v_cvt_pk_bf16_f32 v64, v64, s0
	ds_write_b16 v81, v64 offset:16896
	v_fma_f32 v64, v65, v83, v87
	v_max_f32_e32 v65, v91, v91
	v_max_f32_e64 v64, |v64|, v65
	v_rcp_f32_e32 v64, v64
	v_max_f32_e32 v65, v92, v92
	v_add_u32_e32 v68, s13, v86
	v_mul_f32_e32 v64, v69, v64
	v_cvt_pk_bf16_f32 v64, v64, s0
	ds_write_b16 v80, v64 offset:21648
	v_fma_f32 v64, v66, v84, v88
	v_max_f32_e64 v64, |v64|, v65
	v_rcp_f32_e32 v64, v64
	s_nop 0
	v_mul_f32_e32 v64, v70, v64
	v_cvt_pk_bf16_f32 v64, v64, s0
	ds_write_b16 v80, v64 offset:22176
	v_max_f32_e32 v64, v93, v93
	v_max_f32_e64 v64, |v89|, v64
	v_rcp_f32_e32 v64, v64
	s_nop 0
	v_mul_f32_e32 v64, v71, v64
	v_cvt_pk_bf16_f32 v64, v64, s0
	ds_write_b16 v80, v64 offset:22704
	v_add_u32_e32 v64, s12, v86
	v_add_u32_e32 v86, s42, v86
	ds_read_b128 v[64:67], v64
	ds_read_b128 v[68:71], v68
	ds_read_b128 v[82:85], v82
	ds_read_b128 v[86:89], v86
	s_waitcnt lgkmcnt(1)
	v_fma_f32 v64, v64, v68, v82
	s_waitcnt lgkmcnt(0)
	v_max_f32_e32 v68, v86, v86
	v_max_f32_e64 v64, |v64|, v68
	v_rcp_f32_e32 v64, v64
	v_fmac_f32_e32 v85, v67, v71
	v_or_b32_e32 v82, 0xe0, v217
	v_add_u32_e32 v68, s13, v82
	v_mul_f32_e32 v64, v72, v64
	v_cvt_pk_bf16_f32 v64, v64, s0
	ds_write_b16 v81, v64 offset:21120
	v_fma_f32 v64, v65, v69, v83
	v_max_f32_e32 v65, v87, v87
	v_max_f32_e64 v64, |v64|, v65
	v_rcp_f32_e32 v64, v64
	v_max_f32_e32 v65, v88, v88
	v_add_u32_e32 v72, s15, v82
	v_mul_f32_e32 v64, v73, v64
	v_cvt_pk_bf16_f32 v64, v64, s0
	ds_write_b16 v80, v64 offset:25872
	v_fma_f32 v64, v66, v70, v84
	v_max_f32_e64 v64, |v64|, v65
	v_rcp_f32_e32 v64, v64
	s_nop 0
	v_mul_f32_e32 v64, v74, v64
	v_cvt_pk_bf16_f32 v64, v64, s0
	ds_write_b16 v80, v64 offset:26400
	v_max_f32_e32 v64, v89, v89
	v_max_f32_e64 v64, |v85|, v64
	v_rcp_f32_e32 v64, v64
	s_nop 0
	v_mul_f32_e32 v64, v75, v64
	v_cvt_pk_bf16_f32 v64, v64, s0
	ds_write_b16 v80, v64 offset:26928
	v_add_u32_e32 v64, s12, v82
	v_add_u32_e32 v82, s42, v82
	ds_read_b128 v[64:67], v64
	ds_read_b128 v[68:71], v68
	ds_read_b128 v[72:75], v72
	ds_read_b128 v[82:85], v82
	s_waitcnt lgkmcnt(1)
	v_fma_f32 v64, v64, v68, v72
	s_waitcnt lgkmcnt(0)
	v_max_f32_e32 v68, v82, v82
	v_max_f32_e64 v64, |v64|, v68
	v_rcp_f32_e32 v64, v64
	v_fmac_f32_e32 v75, v67, v71
	v_mad_u32_u24 v72, v215, s93, v208
	v_mul_f32_e32 v64, v76, v64
	v_cvt_pk_bf16_f32 v64, v64, s0
	ds_write_b16 v81, v64 offset:25344
	v_fma_f32 v64, v65, v69, v73
	v_max_f32_e32 v65, v83, v83
	v_max_f32_e64 v64, |v64|, v65
	v_rcp_f32_e32 v64, v64
	v_max_f32_e32 v65, v84, v84
	v_mad_u32_u24 v73, v216, s93, v208
	v_mul_f32_e32 v64, v77, v64
	v_cvt_pk_bf16_f32 v64, v64, s0
	ds_write_b16 v80, v64 offset:30096
	v_fma_f32 v64, v66, v70, v74
	v_max_f32_e64 v64, |v64|, v65
	v_rcp_f32_e32 v64, v64
	v_and_b32_e32 v74, 3, v214
	v_cmp_eq_u32_e32 vcc, 0, v74
	v_mul_f32_e32 v64, v78, v64
	v_cvt_pk_bf16_f32 v64, v64, s0
	ds_write_b16 v80, v64 offset:30624
	v_max_f32_e32 v64, v85, v85
	v_max_f32_e64 v64, |v75|, v64
	v_rcp_f32_e32 v64, v64
	s_nop 0
	v_mul_f32_e32 v64, v79, v64
	v_cvt_pk_bf16_f32 v64, v64, s0
	ds_write_b16 v80, v64 offset:31152
	ds_read_b128 v[64:67], v72 offset:34816
	ds_read_b128 v[68:71], v72 offset:34848
	ds_read_b128 v[76:79], v72 offset:34880
	ds_read_b128 v[80:83], v72 offset:34912
	ds_read_b128 v[84:87], v73 offset:34816
	ds_read_b128 v[88:91], v73 offset:34848
	s_waitcnt lgkmcnt(5)
	v_mfma_f32_32x32x16_bf16 v[0:15], v[64:67], v[168:171], v[0:15]
	ds_read_b128 v[64:67], v73 offset:34880
	s_waitcnt lgkmcnt(5)
	v_mfma_f32_32x32x16_bf16 v[0:15], v[68:71], v[164:167], v[0:15]
	ds_read_b128 v[68:71], v73 offset:34912
	s_waitcnt lgkmcnt(5)
	v_mfma_f32_32x32x16_bf16 v[0:15], v[76:79], v[160:163], v[0:15]
	ds_read_b128 v[76:79], v72 offset:44032
	s_waitcnt lgkmcnt(5)
	v_mfma_f32_32x32x16_bf16 v[0:15], v[80:83], v[156:159], v[0:15]
	ds_read_b128 v[80:83], v72 offset:44064
	s_waitcnt lgkmcnt(5)
	v_mfma_f32_32x32x16_bf16 v[16:31], v[84:87], v[168:171], v[16:31]
	ds_read_b128 v[84:87], v72 offset:44096
	s_waitcnt lgkmcnt(5)
	v_mfma_f32_32x32x16_bf16 v[16:31], v[88:91], v[164:167], v[16:31]
	ds_read_b128 v[88:91], v72 offset:44128
	s_waitcnt lgkmcnt(5)
	v_mfma_f32_32x32x16_bf16 v[16:31], v[64:67], v[160:163], v[16:31]
	ds_read_b128 v[64:67], v72 offset:48640
	s_waitcnt lgkmcnt(5)
	v_mfma_f32_32x32x16_bf16 v[16:31], v[68:71], v[156:159], v[16:31]
	ds_read_b128 v[68:71], v72 offset:48672
	s_waitcnt lgkmcnt(5)
	v_mfma_f32_32x32x16_bf16 v[32:47], v[76:79], v[168:171], v[32:47]
	ds_read_b128 v[76:79], v72 offset:48704
	s_waitcnt lgkmcnt(5)
	v_mfma_f32_32x32x16_bf16 v[32:47], v[80:83], v[164:167], v[32:47]
	ds_read_b128 v[80:83], v72 offset:48736
	s_waitcnt lgkmcnt(5)
	v_mfma_f32_32x32x16_bf16 v[32:47], v[84:87], v[160:163], v[32:47]
	s_waitcnt lgkmcnt(4)
	v_mfma_f32_32x32x16_bf16 v[32:47], v[88:91], v[156:159], v[32:47]
	s_waitcnt lgkmcnt(3)
	v_mfma_f32_32x32x16_bf16 v[48:63], v[64:67], v[168:171], v[48:63]
	s_waitcnt lgkmcnt(2)
	v_mfma_f32_32x32x16_bf16 v[48:63], v[68:71], v[164:167], v[48:63]
	s_waitcnt lgkmcnt(1)
	v_mfma_f32_32x32x16_bf16 v[48:63], v[76:79], v[160:163], v[48:63]
	s_waitcnt lgkmcnt(0)
	v_mfma_f32_32x32x16_bf16 v[48:63], v[80:83], v[156:159], v[48:63]
	v_ashrrev_i32_e32 v64, 2, v214
	v_mul_lo_u32 v65, v64, s93
	v_lshlrev_b32_e32 v66, 5, v74
	v_add3_u32 v65, 0, v65, v66
	ds_read_b128 v[66:69], v65 offset:34816
	ds_read_b128 v[70:73], v65 offset:34832
	s_waitcnt lgkmcnt(1)
	v_lshlrev_b32_e32 v65, 16, v66
	v_and_b32_e32 v66, 0xffff0000, v66
	v_add_f32_e32 v65, v65, v66
	s_waitcnt lgkmcnt(0)
	v_lshlrev_b32_e32 v66, 16, v70
	v_and_b32_e32 v70, 0xffff0000, v70
	v_add_f32_e32 v66, v66, v70
	v_add_f32_e32 v65, v65, v66
	v_lshlrev_b32_e32 v66, 16, v67
	v_and_b32_e32 v67, 0xffff0000, v67
	v_add_f32_e32 v66, v66, v67
	v_lshlrev_b32_e32 v67, 16, v71
	v_and_b32_e32 v70, 0xffff0000, v71
	v_add_f32_e32 v67, v67, v70
	v_add_f32_e32 v65, 0, v65
	v_add_f32_e32 v66, v66, v67
	v_add_f32_e32 v65, v66, v65
	v_lshlrev_b32_e32 v66, 16, v68
	v_and_b32_e32 v67, 0xffff0000, v68
	v_add_f32_e32 v66, v66, v67
	v_lshlrev_b32_e32 v67, 16, v72
	v_and_b32_e32 v68, 0xffff0000, v72
	v_add_f32_e32 v67, v67, v68
	v_add_f32_e32 v66, v66, v67
	v_add_f32_e32 v65, v66, v65
	v_lshlrev_b32_e32 v66, 16, v69
	v_and_b32_e32 v67, 0xffff0000, v69
	v_add_f32_e32 v66, v66, v67
	v_lshlrev_b32_e32 v67, 16, v73
	v_and_b32_e32 v68, 0xffff0000, v73
	v_add_f32_e32 v67, v67, v68
	v_add_f32_e32 v66, v66, v67
	v_add_f32_e32 v65, v66, v65
	ds_bpermute_b32 v66, v189, v65
	s_waitcnt lgkmcnt(0)
	v_add_f32_e32 v65, v65, v66
	ds_bpermute_b32 v66, v191, v65
	s_and_saveexec_b64 s[12:13], vcc
	s_cbranch_execz .LBB0_206
	v_lshl_add_u32 v64, v64, 2, 0
	v_add_u32_e32 v64, 0x21000, v64
	s_waitcnt lgkmcnt(0)
	v_add_f32_e32 v65, v65, v66
	ds_read_b32 v66, v64
	s_waitcnt lgkmcnt(0)
	v_fmac_f32_e32 v65, v96, v66
	ds_write_b32 v64, v65
	s_branch .LBB0_206
